# stack plus: w_in gate-tile epilogue issues its four bias loads before the pre-epilogue barrier
# speedup vs baseline: 1.0120x; 1.0001x over previous
; #define PG8_STAGE(bufoff, gbase, voff) do { _Pragma("unroll") for (int _i = 0; _i < 2; ++_i) \
;         __builtin_amdgcn_global_load_lds((const unsigned*)((const char*)(gbase) + (voff)[_i]), (LAS unsigned*)(lds + (bufoff) + ldsw + _i * 8192), 16, 0, 0); } while (0)
; #define PG8_LDA(dst, b, h) do { _Pragma("unroll") for (int m = 0; m < 4; ++m) _Pragma("unroll") for (int k = 0; k < 2; ++k) dst[m][k] = *(const LAS bf16x8*)(lds + PG8_SA(b, h) + aoff + m * 2048 + k * 1024); } while (0)
; #define PG8_LDB(dst, b, h) do { _Pragma("unroll") for (int n = 0; n < 2; ++n) _Pragma("unroll") for (int k = 0; k < 2; ++k) dst[n][k] = *(const LAS bf16x8*)(lds + PG8_SB(b, h) + boff + n * 2048 + k * 1024); } while (0)
; template <class Epi, bool ALIGN_EPI>
; __device__ __forceinline__ void gemm_phase(LAS unsigned char* lds, const int tid, const Gemm g, const StaticOrder& S, const Epi& E) {
;     ...
;         for (int t = 0; t < nt; t += 2) {
;             if constexpr (Epi::HOOK) { if (t != 0 && (t & 7) == 0) E.hook(acc, cur, (t >> 3) - 1, wr, wc, fr, fq); }
;             const bool last = (t == nt - 2);
;             const char* a1 = cA + (size_t)(t + 1) * kstepA;
;             const char* a2 = last ? nA : cA + (size_t)(t + 2) * kstepA; const char* b2 = last ? nB : cB + (size_t)(t + 2) * kstepB;
;             const char* a3 = a2 + kstepA; const char* b3 = b2 + kstepB;
;             PG8_LDB(B0, 0, 0); PG8_LDB(B1, 0, 1); PG8_SCHED; PG8_LDA(At, 0, 0); PG8_STAGE(PG8_SA(1, 1), a1 + hstepA, voffA);
;             PG8_WAIT_V(8); PG8_WAIT_L(0); PG8_BAR; PG8_MMA(0, 0, At, B0); PG8_MMA(0, 1, At, B1); PG8_BAR; PG8_SCHED;
;             PG8_LDA(At, 0, 1); PG8_STAGE(PG8_SB(0, 0), b2, voffB); PG8_STAGE(PG8_SB(0, 1), b2 + hstepB, voffB); PG8_STAGE(PG8_SA(0, 0), a2, voffA);
;             PG8_WAIT_V(8); PG8_WAIT_L(0); PG8_BAR; PG8_MMA(1, 0, At, B0); PG8_MMA(1, 1, At, B1); PG8_BAR; PG8_SCHED;
;             PG8_LDB(B0, 1, 0); PG8_LDB(B1, 1, 1); PG8_SCHED; PG8_LDA(At, 1, 0); PG8_STAGE(PG8_SA(0, 1), a2 + hstepA, voffA);
;             PG8_WAIT_V(8); PG8_WAIT_L(0); PG8_BAR; PG8_MMA(0, 0, At, B0); PG8_MMA(0, 1, At, B1); PG8_BAR; PG8_SCHED;
;             PG8_LDA(At, 1, 1); PG8_STAGE(PG8_SB(1, 0), b3, voffB); PG8_STAGE(PG8_SB(1, 1), b3 + hstepB, voffB); PG8_STAGE(PG8_SA(1, 0), a3, voffA);
;             PG8_WAIT_V(8); PG8_WAIT_L(0); PG8_BAR; PG8_MMA(1, 0, At, B0); PG8_MMA(1, 1, At, B1); PG8_BAR; PG8_SCHED;
.LBB0_667:
	s_add_u32 s22, s20, 0xfff80080
	s_addc_u32 s23, s21, -1
	s_add_i32 s49, 0, 0x10000
	s_cmp_eq_u32 s19, 28
	s_cselect_b32 s25, s15, s23
	s_cselect_b32 s24, s14, s22
	v_add_u32_e32 v0, s49, v173
	s_cselect_b32 s23, s17, s13
	s_cselect_b32 s22, s16, s11
	s_add_i32 s52, 0, 0x14000
	ds_read_b128 v[130:133], v0
	ds_read_b128 v[134:137], v0 offset:1024
	ds_read_b128 v[138:141], v0 offset:2048
	ds_read_b128 v[142:145], v0 offset:3072
	v_add_u32_e32 v0, s52, v173
	ds_read_b128 v[158:161], v0
	ds_read_b128 v[162:165], v0 offset:1024
	ds_read_b128 v[166:169], v0 offset:2048
	ds_read_b128 v[178:181], v0 offset:3072
	v_lshl_add_u64 v[170:171], s[20:21], 0, v[156:157]
	s_add_i32 m0, s28, 0xc000
	ds_read_b128 v[182:185], v176
	ds_read_b128 v[186:189], v176 offset:1024
	ds_read_b128 v[190:193], v176 offset:2048
	ds_read_b128 v[208:211], v176 offset:3072
	ds_read_b128 v[212:215], v176 offset:4096
	ds_read_b128 v[216:219], v176 offset:5120
	ds_read_b128 v[220:223], v176 offset:6144
	ds_read_b128 v[240:243], v176 offset:7168
	global_load_lds_dwordx4 v[170:171], off
	v_lshl_add_u64 v[170:171], s[20:21], 0, v[154:155]
	s_add_i32 m0, s28, 0xe000
	s_nop 0
	global_load_lds_dwordx4 v[170:171], off
	s_sub_u32 s98, s20, 0x80000
	s_subb_u32 s99, s21, 0
	v_lshl_add_u64 v[170:171], s[98:99], 0, v[156:157]
	s_mov_b32 m0, s34
	s_nop 0
	global_load_lds_dwordx4 v[170:171], off
	v_lshl_add_u64 v[170:171], s[98:99], 0, v[154:155]
	s_mov_b32 m0, s35
	s_nop 0
	global_load_lds_dwordx4 v[170:171], off
	s_waitcnt vmcnt(8)
	s_waitcnt lgkmcnt(0)
	s_barrier
	s_waitcnt lgkmcnt(0)
	v_mfma_f32_16x16x32_bf16 v[126:129], v[130:133], v[182:185], v[126:129]
	v_mfma_f32_16x16x32_bf16 v[122:125], v[138:141], v[182:185], v[122:125]
	v_mfma_f32_16x16x32_bf16 v[118:121], v[130:133], v[190:193], v[118:121]
	v_mfma_f32_16x16x32_bf16 v[114:117], v[138:141], v[190:193], v[114:117]
	v_mfma_f32_16x16x32_bf16 v[102:105], v[130:133], v[212:215], v[102:105]
	v_mfma_f32_16x16x32_bf16 v[98:101], v[138:141], v[212:215], v[98:101]
	v_mfma_f32_16x16x32_bf16 v[86:89], v[130:133], v[220:223], v[86:89]
	v_mfma_f32_16x16x32_bf16 v[82:85], v[138:141], v[220:223], v[82:85]
	v_mfma_f32_16x16x32_bf16 v[126:129], v[134:137], v[186:189], v[126:129]
	v_mfma_f32_16x16x32_bf16 v[122:125], v[142:145], v[186:189], v[122:125]
	v_mfma_f32_16x16x32_bf16 v[118:121], v[134:137], v[208:211], v[118:121]
	v_mfma_f32_16x16x32_bf16 v[114:117], v[142:145], v[208:211], v[114:117]
	v_mfma_f32_16x16x32_bf16 v[102:105], v[134:137], v[216:219], v[102:105]
	v_mfma_f32_16x16x32_bf16 v[98:101], v[142:145], v[216:219], v[98:101]
	v_mfma_f32_16x16x32_bf16 v[86:89], v[134:137], v[240:243], v[86:89]
	v_mfma_f32_16x16x32_bf16 v[82:85], v[142:145], v[240:243], v[82:85]
	v_mfma_f32_16x16x32_bf16 v[110:113], v[158:161], v[182:185], v[110:113]
	v_mfma_f32_16x16x32_bf16 v[106:109], v[166:169], v[182:185], v[106:109]
	v_mfma_f32_16x16x32_bf16 v[94:97], v[158:161], v[190:193], v[94:97]
	v_mfma_f32_16x16x32_bf16 v[90:93], v[166:169], v[190:193], v[90:93]
	v_mfma_f32_16x16x32_bf16 v[78:81], v[158:161], v[212:215], v[78:81]
	v_mfma_f32_16x16x32_bf16 v[74:77], v[166:169], v[212:215], v[74:77]
	v_mfma_f32_16x16x32_bf16 v[70:73], v[158:161], v[220:223], v[70:73]
	v_mfma_f32_16x16x32_bf16 v[66:69], v[166:169], v[220:223], v[66:69]
	v_mfma_f32_16x16x32_bf16 v[110:113], v[162:165], v[186:189], v[110:113]
	v_mfma_f32_16x16x32_bf16 v[106:109], v[178:181], v[186:189], v[106:109]
	v_mfma_f32_16x16x32_bf16 v[94:97], v[162:165], v[208:211], v[94:97]
	v_mfma_f32_16x16x32_bf16 v[90:93], v[178:181], v[208:211], v[90:93]
	v_mfma_f32_16x16x32_bf16 v[78:81], v[162:165], v[216:219], v[78:81]
	v_mfma_f32_16x16x32_bf16 v[74:77], v[178:181], v[216:219], v[74:77]
	v_mfma_f32_16x16x32_bf16 v[70:73], v[162:165], v[240:243], v[70:73]
	v_mfma_f32_16x16x32_bf16 v[66:69], v[178:181], v[240:243], v[66:69]
	s_barrier
	s_add_i32 s49, s49, s27
	v_lshl_add_u64 v[170:171], s[22:23], 0, v[148:149]
	s_mov_b32 m0, s49
	ds_read_b128 v[182:185], v176 offset:16384
	ds_read_b128 v[186:189], v176 offset:17408
	ds_read_b128 v[190:193], v176 offset:18432
	ds_read_b128 v[208:211], v176 offset:19456
	ds_read_b128 v[212:215], v176 offset:20480
	ds_read_b128 v[216:219], v176 offset:21504
	ds_read_b128 v[220:223], v176 offset:22528
	ds_read_b128 v[240:243], v176 offset:23552
	global_load_lds_dwordx4 v[170:171], off
	s_add_i32 m0, s49, 0x2000
	s_add_u32 s54, s22, 0x80000
	v_lshl_add_u64 v[194:195], s[22:23], 0, v[152:153]
	s_addc_u32 s55, s23, 0
	s_add_i32 s49, s52, s27
	global_load_lds_dwordx4 v[194:195], off
	v_lshl_add_u64 v[224:225], s[54:55], 0, v[148:149]
	s_mov_b32 m0, s49
	v_lshl_add_u64 v[244:245], s[24:25], 0, v[150:151]
	global_load_lds_dwordx4 v[224:225], off
	v_lshl_add_u64 v[224:225], s[54:55], 0, v[152:153]
	s_add_i32 m0, s49, 0x2000
	s_nop 0
	global_load_lds_dwordx4 v[224:225], off
	v_lshl_add_u64 v[224:225], s[24:25], 0, v[146:147]
	s_waitcnt vmcnt(4)
	s_waitcnt lgkmcnt(0)
	s_barrier
; #define PG8_STAGE(bufoff, gbase, voff) do { _Pragma("unroll") for (int _i = 0; _i < 2; ++_i) \
;         __builtin_amdgcn_global_load_lds((const unsigned*)((const char*)(gbase) + (voff)[_i]), (LAS unsigned*)(lds + (bufoff) + ldsw + _i * 8192), 16, 0, 0); } while (0)
; #define PG8_LDA(dst, b, h) do { _Pragma("unroll") for (int m = 0; m < 4; ++m) _Pragma("unroll") for (int k = 0; k < 2; ++k) dst[m][k] = *(const LAS bf16x8*)(lds + PG8_SA(b, h) + aoff + m * 2048 + k * 1024); } while (0)
; #define PG8_LDB(dst, b, h) do { _Pragma("unroll") for (int n = 0; n < 2; ++n) _Pragma("unroll") for (int k = 0; k < 2; ++k) dst[n][k] = *(const LAS bf16x8*)(lds + PG8_SB(b, h) + boff + n * 2048 + k * 1024); } while (0)
; #define PG8_MMA(ai, bj, At, Bt) do { __builtin_amdgcn_s_setprio(1); _Pragma("unroll") for (int m = 0; m < 4; ++m) _Pragma("unroll") for (int n = 0; n < 2; ++n) _Pragma("unroll") for (int k = 0; k < 2; ++k) \
;         acc[ai][bj][m][n] = __builtin_amdgcn_mfma_f32_16x16x32_bf16(Bt[n][k], At[m][k], acc[ai][bj][m][n], 0, 0, 0); __builtin_amdgcn_s_setprio(0); } while (0)
; #define PG8_WAIT_V(n) asm volatile("s_waitcnt vmcnt(" #n ")" ::: "memory")
; template <class Epi, bool ALIGN_EPI>
; __device__ __forceinline__ void gemm_phase(LAS unsigned char* lds, const int tid, const Gemm g, const StaticOrder& S, const Epi& E) {
;     ...
;             PG8_LDB(B0, 0, 0); PG8_LDB(B1, 0, 1); PG8_SCHED; PG8_LDA(At, 0, 0); PG8_STAGE(PG8_SA(1, 1), a1 + hstepA, voffA);
;             PG8_WAIT_V(8); PG8_WAIT_L(0); PG8_BAR; PG8_MMA(0, 0, At, B0); PG8_MMA(0, 1, At, B1); PG8_BAR; PG8_SCHED;
;             PG8_LDA(At, 0, 1); PG8_STAGE(PG8_SB(0, 0), b2, voffB); PG8_STAGE(PG8_SB(0, 1), b2 + hstepB, voffB); PG8_STAGE(PG8_SA(0, 0), a2, voffA);
;             PG8_WAIT_V(8); PG8_WAIT_L(0); PG8_BAR; PG8_MMA(1, 0, At, B0); PG8_MMA(1, 1, At, B1); PG8_BAR; PG8_SCHED;
;             PG8_LDB(B0, 1, 0); PG8_LDB(B1, 1, 1); PG8_SCHED; PG8_LDA(At, 1, 0); PG8_STAGE(PG8_SA(0, 1), a2 + hstepA, voffA);
;             PG8_WAIT_V(8); PG8_WAIT_L(0); PG8_BAR; PG8_MMA(0, 0, At, B0); PG8_MMA(0, 1, At, B1); PG8_BAR; PG8_SCHED;
;             PG8_LDA(At, 1, 1); PG8_STAGE(PG8_SB(1, 0), b3, voffB); PG8_STAGE(PG8_SB(1, 1), b3 + hstepB, voffB); PG8_STAGE(PG8_SA(1, 0), a3, voffA);
;             PG8_WAIT_V(8); PG8_WAIT_L(0); PG8_BAR; PG8_MMA(1, 0, At, B0); PG8_MMA(1, 1, At, B1); PG8_BAR; PG8_SCHED;
	s_waitcnt lgkmcnt(0)
	v_mfma_f32_16x16x32_bf16 v[62:65], v[130:133], v[182:185], v[62:65]
	v_mfma_f32_16x16x32_bf16 v[58:61], v[138:141], v[182:185], v[58:61]
	v_mfma_f32_16x16x32_bf16 v[54:57], v[130:133], v[190:193], v[54:57]
	v_mfma_f32_16x16x32_bf16 v[50:53], v[138:141], v[190:193], v[50:53]
	v_mfma_f32_16x16x32_bf16 v[38:41], v[130:133], v[212:215], v[38:41]
	v_mfma_f32_16x16x32_bf16 v[34:37], v[138:141], v[212:215], v[34:37]
	v_mfma_f32_16x16x32_bf16 v[22:25], v[130:133], v[220:223], v[22:25]
	v_mfma_f32_16x16x32_bf16 v[18:21], v[138:141], v[220:223], v[18:21]
	v_mfma_f32_16x16x32_bf16 v[62:65], v[134:137], v[186:189], v[62:65]
	v_mfma_f32_16x16x32_bf16 v[58:61], v[142:145], v[186:189], v[58:61]
	v_mfma_f32_16x16x32_bf16 v[54:57], v[134:137], v[208:211], v[54:57]
	v_mfma_f32_16x16x32_bf16 v[50:53], v[142:145], v[208:211], v[50:53]
	v_mfma_f32_16x16x32_bf16 v[38:41], v[134:137], v[216:219], v[38:41]
	v_mfma_f32_16x16x32_bf16 v[34:37], v[142:145], v[216:219], v[34:37]
	v_mfma_f32_16x16x32_bf16 v[22:25], v[134:137], v[240:243], v[22:25]
	v_mfma_f32_16x16x32_bf16 v[18:21], v[142:145], v[240:243], v[18:21]
	v_mfma_f32_16x16x32_bf16 v[46:49], v[158:161], v[182:185], v[46:49]
	v_mfma_f32_16x16x32_bf16 v[42:45], v[166:169], v[182:185], v[42:45]
	v_mfma_f32_16x16x32_bf16 v[30:33], v[158:161], v[190:193], v[30:33]
	v_mfma_f32_16x16x32_bf16 v[26:29], v[166:169], v[190:193], v[26:29]
	v_mfma_f32_16x16x32_bf16 v[14:17], v[158:161], v[212:215], v[14:17]
	v_mfma_f32_16x16x32_bf16 v[10:13], v[166:169], v[212:215], v[10:13]
	v_mfma_f32_16x16x32_bf16 v[6:9], v[158:161], v[220:223], v[6:9]
	v_mfma_f32_16x16x32_bf16 v[2:5], v[166:169], v[220:223], v[2:5]
	v_mfma_f32_16x16x32_bf16 v[46:49], v[162:165], v[186:189], v[46:49]
	v_mfma_f32_16x16x32_bf16 v[42:45], v[178:181], v[186:189], v[42:45]
	v_mfma_f32_16x16x32_bf16 v[30:33], v[162:165], v[208:211], v[30:33]
	v_mfma_f32_16x16x32_bf16 v[26:29], v[178:181], v[208:211], v[26:29]
	v_mfma_f32_16x16x32_bf16 v[14:17], v[162:165], v[216:219], v[14:17]
	v_mfma_f32_16x16x32_bf16 v[10:13], v[178:181], v[216:219], v[10:13]
	v_mfma_f32_16x16x32_bf16 v[6:9], v[162:165], v[240:243], v[6:9]
	v_mfma_f32_16x16x32_bf16 v[2:5], v[178:181], v[240:243], v[2:5]
	s_barrier
	s_add_i32 s49, 0, 0x18000
	v_add_u32_e32 v0, s49, v173
	s_add_i32 s52, 0, 0x1c000
	ds_read_b128 v[130:133], v0
	ds_read_b128 v[134:137], v0 offset:1024
	ds_read_b128 v[138:141], v0 offset:2048
	ds_read_b128 v[142:145], v0 offset:3072
	v_add_u32_e32 v0, s52, v173
	ds_read_b128 v[158:161], v0
	ds_read_b128 v[162:165], v0 offset:1024
	ds_read_b128 v[166:169], v0 offset:2048
	ds_read_b128 v[178:181], v0 offset:3072
	s_mov_b32 m0, s28
	s_nop 0
	global_load_lds_dwordx4 v[224:225], off
	s_mov_b32 m0, s29
	s_nop 0
	global_load_lds_dwordx4 v[244:245], off
	s_add_u32 s24, s24, 0x80000
	s_addc_u32 s25, s25, 0
	s_mov_b32 m0, s30
	v_lshl_add_u64 v[246:247], s[24:25], 0, v[146:147]
	ds_read_b128 v[182:185], v176 offset:32768
	ds_read_b128 v[186:189], v176 offset:33792
	ds_read_b128 v[190:193], v176 offset:34816
	ds_read_b128 v[208:211], v176 offset:35840
	ds_read_b128 v[212:215], v176 offset:36864
	ds_read_b128 v[216:219], v176 offset:37888
	ds_read_b128 v[220:223], v176 offset:38912
	ds_read_b128 v[240:243], v176 offset:39936
	global_load_lds_dwordx4 v[246:247], off
	v_lshl_add_u64 v[246:247], s[24:25], 0, v[150:151]
	s_mov_b32 m0, s31
	s_nop 0
	global_load_lds_dwordx4 v[246:247], off
	s_waitcnt vmcnt(8)
	s_waitcnt lgkmcnt(0)
	s_barrier
	s_waitcnt lgkmcnt(0)
	v_mfma_f32_16x16x32_bf16 v[126:129], v[130:133], v[182:185], v[126:129]
	v_mfma_f32_16x16x32_bf16 v[122:125], v[138:141], v[182:185], v[122:125]
	v_mfma_f32_16x16x32_bf16 v[118:121], v[130:133], v[190:193], v[118:121]
	v_mfma_f32_16x16x32_bf16 v[114:117], v[138:141], v[190:193], v[114:117]
	v_mfma_f32_16x16x32_bf16 v[102:105], v[130:133], v[212:215], v[102:105]
	v_mfma_f32_16x16x32_bf16 v[98:101], v[138:141], v[212:215], v[98:101]
	v_mfma_f32_16x16x32_bf16 v[86:89], v[130:133], v[220:223], v[86:89]
	v_mfma_f32_16x16x32_bf16 v[82:85], v[138:141], v[220:223], v[82:85]
	v_mfma_f32_16x16x32_bf16 v[126:129], v[134:137], v[186:189], v[126:129]
	v_mfma_f32_16x16x32_bf16 v[122:125], v[142:145], v[186:189], v[122:125]
	v_mfma_f32_16x16x32_bf16 v[118:121], v[134:137], v[208:211], v[118:121]
	v_mfma_f32_16x16x32_bf16 v[114:117], v[142:145], v[208:211], v[114:117]
	v_mfma_f32_16x16x32_bf16 v[102:105], v[134:137], v[216:219], v[102:105]
	v_mfma_f32_16x16x32_bf16 v[98:101], v[142:145], v[216:219], v[98:101]
	v_mfma_f32_16x16x32_bf16 v[86:89], v[134:137], v[240:243], v[86:89]
	v_mfma_f32_16x16x32_bf16 v[82:85], v[142:145], v[240:243], v[82:85]
	v_mfma_f32_16x16x32_bf16 v[110:113], v[158:161], v[182:185], v[110:113]
	v_mfma_f32_16x16x32_bf16 v[106:109], v[166:169], v[182:185], v[106:109]
	v_mfma_f32_16x16x32_bf16 v[94:97], v[158:161], v[190:193], v[94:97]
	v_mfma_f32_16x16x32_bf16 v[90:93], v[166:169], v[190:193], v[90:93]
	v_mfma_f32_16x16x32_bf16 v[78:81], v[158:161], v[212:215], v[78:81]
	v_mfma_f32_16x16x32_bf16 v[74:77], v[166:169], v[212:215], v[74:77]
	v_mfma_f32_16x16x32_bf16 v[70:73], v[158:161], v[220:223], v[70:73]
	v_mfma_f32_16x16x32_bf16 v[66:69], v[166:169], v[220:223], v[66:69]
	v_mfma_f32_16x16x32_bf16 v[110:113], v[162:165], v[186:189], v[110:113]
	v_mfma_f32_16x16x32_bf16 v[106:109], v[178:181], v[186:189], v[106:109]
	v_mfma_f32_16x16x32_bf16 v[94:97], v[162:165], v[208:211], v[94:97]
	v_mfma_f32_16x16x32_bf16 v[90:93], v[178:181], v[208:211], v[90:93]
	v_mfma_f32_16x16x32_bf16 v[78:81], v[162:165], v[216:219], v[78:81]
	v_mfma_f32_16x16x32_bf16 v[74:77], v[178:181], v[216:219], v[74:77]
	v_mfma_f32_16x16x32_bf16 v[70:73], v[162:165], v[240:243], v[70:73]
	v_mfma_f32_16x16x32_bf16 v[66:69], v[178:181], v[240:243], v[66:69]
	s_barrier
; #define GAS __attribute__((address_space(1)))
; #define PG8_STAGE(bufoff, gbase, voff) do { _Pragma("unroll") for (int _i = 0; _i < 2; ++_i) \
;         __builtin_amdgcn_global_load_lds((const unsigned*)((const char*)(gbase) + (voff)[_i]), (LAS unsigned*)(lds + (bufoff) + ldsw + _i * 8192), 16, 0, 0); } while (0)
; #define PG8_LDA(dst, b, h) do { _Pragma("unroll") for (int m = 0; m < 4; ++m) _Pragma("unroll") for (int k = 0; k < 2; ++k) dst[m][k] = *(const LAS bf16x8*)(lds + PG8_SA(b, h) + aoff + m * 2048 + k * 1024); } while (0)
; #define PG8_MMA(ai, bj, At, Bt) do { __builtin_amdgcn_s_setprio(1); _Pragma("unroll") for (int m = 0; m < 4; ++m) _Pragma("unroll") for (int n = 0; n < 2; ++n) _Pragma("unroll") for (int k = 0; k < 2; ++k) \
;         acc[ai][bj][m][n] = __builtin_amdgcn_mfma_f32_16x16x32_bf16(Bt[n][k], At[m][k], acc[ai][bj][m][n], 0, 0, 0); __builtin_amdgcn_s_setprio(0); } while (0)
; #define PG8_WAIT_V(n) asm volatile("s_waitcnt vmcnt(" #n ")" ::: "memory")
; #define PG8_WAIT_L(n) asm volatile("s_waitcnt lgkmcnt(" #n ")" ::: "memory")
; #define PG8_BAR __builtin_amdgcn_s_barrier()
; #define PG8_SCHED __builtin_amdgcn_sched_barrier(0)
; template <class Epi, bool ALIGN_EPI>
; __device__ __forceinline__ void gemm_phase(LAS unsigned char* lds, const int tid, const Gemm g, const StaticOrder& S, const Epi& E) {
;     ...
;             PG8_WAIT_V(8); PG8_WAIT_L(0); PG8_BAR; PG8_MMA(0, 0, At, B0); PG8_MMA(0, 1, At, B1); PG8_BAR; PG8_SCHED;
;             PG8_LDA(At, 1, 1); PG8_STAGE(PG8_SB(1, 0), b3, voffB); PG8_STAGE(PG8_SB(1, 1), b3 + hstepB, voffB); PG8_STAGE(PG8_SA(1, 0), a3, voffA);
;             PG8_WAIT_V(8); PG8_WAIT_L(0); PG8_BAR; PG8_MMA(1, 0, At, B0); PG8_MMA(1, 1, At, B1); PG8_BAR; PG8_SCHED;
;         }
;         if constexpr (ALIGN_EPI) { if (wr == 0) PG8_BAR; }
;     __device__ __forceinline__ void operator()(const f32x4 (&acc)[2][2][4][2], const Unit& u, int wr, int wc, int fr, int fq) const {
;     ...
;             const int col0 = colt - ZW + wc * 32 + 8 * fq;
;             f32x4 bv[2][2];
; #pragma unroll
;             for (int bj = 0; bj < 2; ++bj)
; #pragma unroll
;                 for (int n = 0; n < 2; ++n) bv[bj][n] = *(const GAS f32x4*)(bgate + col0 + bj * HALF + 4 * n);
	s_add_i32 s24, s49, s27
	v_lshl_add_u64 v[170:171], v[170:171], 0, s[42:43]
	s_mov_b32 m0, s24
	ds_read_b128 v[182:185], v176 offset:49152
	ds_read_b128 v[186:189], v176 offset:50176
	ds_read_b128 v[190:193], v176 offset:51200
	ds_read_b128 v[208:211], v176 offset:52224
	ds_read_b128 v[212:215], v176 offset:53248
	ds_read_b128 v[216:219], v176 offset:54272
	ds_read_b128 v[220:223], v176 offset:55296
	ds_read_b128 v[240:243], v176 offset:56320
	global_load_lds_dwordx4 v[170:171], off
	s_add_i32 m0, s24, 0x2000
	s_add_u32 s22, s22, 0x80080
	v_lshl_add_u64 v[170:171], v[194:195], 0, s[42:43]
	s_addc_u32 s23, s23, 0
	s_add_i32 s24, s52, s27
	global_load_lds_dwordx4 v[170:171], off
	v_lshl_add_u64 v[170:171], s[22:23], 0, v[148:149]
	s_mov_b32 m0, s24
	s_nop 0
	global_load_lds_dwordx4 v[170:171], off
	v_lshl_add_u64 v[170:171], s[22:23], 0, v[152:153]
	s_add_i32 m0, s24, 0x2000
	s_nop 0
	global_load_lds_dwordx4 v[170:171], off
	s_waitcnt vmcnt(4)
	s_waitcnt lgkmcnt(0)
	s_barrier
	s_waitcnt lgkmcnt(0)
	v_mfma_f32_16x16x32_bf16 v[62:65], v[130:133], v[182:185], v[62:65]
	v_mfma_f32_16x16x32_bf16 v[58:61], v[138:141], v[182:185], v[58:61]
	v_mfma_f32_16x16x32_bf16 v[54:57], v[130:133], v[190:193], v[54:57]
	v_mfma_f32_16x16x32_bf16 v[50:53], v[138:141], v[190:193], v[50:53]
	v_mfma_f32_16x16x32_bf16 v[38:41], v[130:133], v[212:215], v[38:41]
	v_mfma_f32_16x16x32_bf16 v[34:37], v[138:141], v[212:215], v[34:37]
	v_mfma_f32_16x16x32_bf16 v[22:25], v[130:133], v[220:223], v[22:25]
	v_mfma_f32_16x16x32_bf16 v[18:21], v[138:141], v[220:223], v[18:21]
	v_mfma_f32_16x16x32_bf16 v[62:65], v[134:137], v[186:189], v[62:65]
	v_mfma_f32_16x16x32_bf16 v[58:61], v[142:145], v[186:189], v[58:61]
	v_mfma_f32_16x16x32_bf16 v[54:57], v[134:137], v[208:211], v[54:57]
	v_mfma_f32_16x16x32_bf16 v[50:53], v[142:145], v[208:211], v[50:53]
	v_mfma_f32_16x16x32_bf16 v[38:41], v[134:137], v[216:219], v[38:41]
	v_mfma_f32_16x16x32_bf16 v[34:37], v[142:145], v[216:219], v[34:37]
	v_mfma_f32_16x16x32_bf16 v[22:25], v[134:137], v[240:243], v[22:25]
	v_mfma_f32_16x16x32_bf16 v[18:21], v[142:145], v[240:243], v[18:21]
	v_mfma_f32_16x16x32_bf16 v[46:49], v[158:161], v[182:185], v[46:49]
	v_mfma_f32_16x16x32_bf16 v[42:45], v[166:169], v[182:185], v[42:45]
	v_mfma_f32_16x16x32_bf16 v[30:33], v[158:161], v[190:193], v[30:33]
	v_mfma_f32_16x16x32_bf16 v[26:29], v[166:169], v[190:193], v[26:29]
	v_mfma_f32_16x16x32_bf16 v[14:17], v[158:161], v[212:215], v[14:17]
	v_mfma_f32_16x16x32_bf16 v[10:13], v[166:169], v[212:215], v[10:13]
	v_mfma_f32_16x16x32_bf16 v[6:9], v[158:161], v[220:223], v[6:9]
	v_mfma_f32_16x16x32_bf16 v[2:5], v[166:169], v[220:223], v[2:5]
	v_mfma_f32_16x16x32_bf16 v[46:49], v[162:165], v[186:189], v[46:49]
	v_mfma_f32_16x16x32_bf16 v[42:45], v[178:181], v[186:189], v[42:45]
	v_mfma_f32_16x16x32_bf16 v[30:33], v[162:165], v[208:211], v[30:33]
	v_mfma_f32_16x16x32_bf16 v[26:29], v[178:181], v[208:211], v[26:29]
	v_mfma_f32_16x16x32_bf16 v[14:17], v[162:165], v[216:219], v[14:17]
	v_mfma_f32_16x16x32_bf16 v[10:13], v[178:181], v[216:219], v[10:13]
	v_mfma_f32_16x16x32_bf16 v[6:9], v[162:165], v[240:243], v[6:9]
	v_mfma_f32_16x16x32_bf16 v[2:5], v[178:181], v[240:243], v[2:5]
	s_barrier
	s_add_i32 s19, s19, 2
	s_add_u32 s11, s11, 0x100
	s_addc_u32 s13, s13, 0
	s_add_u32 s20, s20, 0x100
	s_addc_u32 s21, s21, 0
	s_cmp_gt_u32 s19, 29
	s_cbranch_scc0 .LBB0_667
	s_lshl_b32 s11, s41, 8
	s_cmp_gt_i32 s41, 16
	s_cbranch_scc0 .Lwin_nobias
	v_add_u32_e32 v0, s11, v175
	v_lshl_add_u64 v[134:135], v[0:1], 2, s[6:7]
	global_load_dwordx4 v[138:141], v[134:135], off offset:16
	global_load_dwordx4 v[142:145], v[134:135], off
	global_load_dwordx4 v[130:133], v[134:135], off offset:528
	s_nop 0
	global_load_dwordx4 v[134:137], v[134:135], off offset:512
.Lwin_nobias:
	s_and_b64 vcc, exec, s[8:9]
	s_cbranch_vccz .LBB0_670
	s_barrier
.LBB0_670:
	v_lshl_add_u32 v158, s18, 8, v172
	s_lshl_b32 s11, s41, 8
	s_mov_b64 s[18:19], -1
	s_cmp_gt_i32 s41, 16
	v_or_b32_e32 v164, 16, v158
	v_or_b32_e32 v162, 32, v158
	v_or_b32_e32 v160, 48, v158
	s_cbranch_scc0 .LBB0_672
	v_ashrrev_i32_e32 v159, 31, v158
	v_lshlrev_b64 v[166:167], 14, v[158:159]
	v_lshlrev_b64 v[168:169], 1, v[0:1]
	v_lshl_add_u64 v[166:167], s[88:89], 0, v[166:167]
	v_lshl_add_u64 v[166:167], v[166:167], 0, v[168:169]
	s_mov_b32 s13, 0x200000
	s_mov_b64 s[18:19], 0x200000
	s_waitcnt vmcnt(0)
; #define GAS __attribute__((address_space(1)))
; DI unsigned pk2(float lo, float hi) { f32x2 v = {lo, hi}; bf16x2_t b = __builtin_convertvector(v, bf16x2_t); return __builtin_bit_cast(unsigned, b); }
; DI float fast_exp2(float x) { return __builtin_amdgcn_exp2f(x); }
; DI float fast_rcp(float x) { return __builtin_amdgcn_rcpf(x); }
;     __device__ __forceinline__ void operator()(const f32x4 (&acc)[2][2][4][2], const Unit& u, int wr, int wc, int fr, int fq) const {
;     ...
;             for (int ai = 0; ai < 2; ++ai)
; #pragma unroll
;                 for (int m = 0; m < 4; ++m) { bf16_t* rowp = Gp + (size_t)(row0 + ai * HALF + m * 16) * GW + col0;
; #pragma unroll
;                     for (int bj = 0; bj < 2; ++bj) { f32x4 v0 = acc[ai][bj][m][0] + bv[bj][0], v1 = acc[ai][bj][m][1] + bv[bj][1];
; #pragma unroll
;                         for (int e = 0; e < 4; ++e) { float a = fminf(fmaxf(v0[e], -30.f), 30.f), b = fminf(fmaxf(v1[e], -30.f), 30.f);
;                             v0[e] = fast_rcp(1.f + fast_exp2(-a * LOG2E)); v1[e] = fast_rcp(1.f + fast_exp2(-b * LOG2E)); }
;                         u32x4 w; w.x = pk2(v0[0], v0[1]); w.y = pk2(v0[2], v0[3]); w.z = pk2(v1[0], v1[1]); w.w = pk2(v1[2], v1[3]);
;                         *(GAS u32x4*)(rowp + bj * HALF) = w; } }
	v_pk_add_f32 v[180:181], v[124:125], v[140:141]
	v_pk_add_f32 v[170:171], v[128:129], v[144:145]
	v_pk_add_f32 v[178:179], v[126:127], v[142:143]
	v_pk_add_f32 v[182:183], v[122:123], v[138:139]
	v_med3_f32 v0, v178, s3, v236
	v_med3_f32 v159, v182, s3, v236
	v_med3_f32 v161, v179, s3, v236
	v_med3_f32 v163, v183, s3, v236
	v_med3_f32 v165, v170, s3, v236
	v_med3_f32 v170, v180, s3, v236
	v_med3_f32 v171, v171, s3, v236
	v_med3_f32 v177, v181, s3, v236
	v_mul_f32_e32 v0, 0xbfb8aa3b, v0
	v_mul_f32_e32 v159, 0xbfb8aa3b, v159
	v_mul_f32_e32 v161, 0xbfb8aa3b, v161
	v_mul_f32_e32 v163, 0xbfb8aa3b, v163
	v_mul_f32_e32 v165, 0xbfb8aa3b, v165
	v_mul_f32_e32 v170, 0xbfb8aa3b, v170
	v_mul_f32_e32 v171, 0xbfb8aa3b, v171
	v_mul_f32_e32 v177, 0xbfb8aa3b, v177
	v_exp_f32_e32 v0, v0
	v_exp_f32_e32 v159, v159
	v_exp_f32_e32 v161, v161
	v_exp_f32_e32 v163, v163
	v_exp_f32_e32 v165, v165
	v_exp_f32_e32 v170, v170
	v_exp_f32_e32 v171, v171
	v_exp_f32_e32 v177, v177
	v_add_f32_e32 v0, 1.0, v0
	v_add_f32_e32 v159, 1.0, v159
	v_add_f32_e32 v161, 1.0, v161
	v_add_f32_e32 v163, 1.0, v163
	v_add_f32_e32 v165, 1.0, v165
	v_add_f32_e32 v170, 1.0, v170
	v_add_f32_e32 v171, 1.0, v171
	v_add_f32_e32 v177, 1.0, v177
	v_rcp_f32_e32 v0, v0
	v_rcp_f32_e32 v159, v159
	v_rcp_f32_e32 v161, v161
	v_rcp_f32_e32 v163, v163
	v_rcp_f32_e32 v165, v165
	v_rcp_f32_e32 v170, v170
	v_rcp_f32_e32 v171, v171
	v_rcp_f32_e32 v177, v177
	v_cvt_pk_bf16_f32 v178, v0, v161
	v_cvt_pk_bf16_f32 v180, v159, v163
	v_cvt_pk_bf16_f32 v179, v165, v171
	v_cvt_pk_bf16_f32 v181, v170, v177
	global_store_dwordx4 v[166:167], v[178:181], off
	v_pk_add_f32 v[170:171], v[112:113], v[136:137]
	v_pk_add_f32 v[182:183], v[106:107], v[130:131]
	v_pk_add_f32 v[178:179], v[110:111], v[134:135]
	v_pk_add_f32 v[180:181], v[108:109], v[132:133]
	v_med3_f32 v0, v178, s3, v236
	v_med3_f32 v159, v182, s3, v236
	v_med3_f32 v161, v179, s3, v236
	v_med3_f32 v163, v183, s3, v236
	v_med3_f32 v165, v170, s3, v236
	v_med3_f32 v170, v180, s3, v236
	v_med3_f32 v171, v171, s3, v236
	v_med3_f32 v177, v181, s3, v236
	v_mul_f32_e32 v0, 0xbfb8aa3b, v0
	v_mul_f32_e32 v159, 0xbfb8aa3b, v159
	v_mul_f32_e32 v161, 0xbfb8aa3b, v161
	v_mul_f32_e32 v163, 0xbfb8aa3b, v163
	v_mul_f32_e32 v165, 0xbfb8aa3b, v165
	v_mul_f32_e32 v170, 0xbfb8aa3b, v170
	v_mul_f32_e32 v171, 0xbfb8aa3b, v171
	v_mul_f32_e32 v177, 0xbfb8aa3b, v177
	v_exp_f32_e32 v0, v0
	v_exp_f32_e32 v159, v159
	v_exp_f32_e32 v161, v161
	v_exp_f32_e32 v163, v163
	v_exp_f32_e32 v165, v165
	v_exp_f32_e32 v170, v170
	v_exp_f32_e32 v171, v171
	v_exp_f32_e32 v177, v177
	v_add_f32_e32 v0, 1.0, v0
	v_add_f32_e32 v159, 1.0, v159
	v_add_f32_e32 v161, 1.0, v161
	v_add_f32_e32 v163, 1.0, v163
	v_add_f32_e32 v165, 1.0, v165
	v_add_f32_e32 v170, 1.0, v170
	v_add_f32_e32 v171, 1.0, v171
	v_add_f32_e32 v177, 1.0, v177
	v_rcp_f32_e32 v0, v0
	v_rcp_f32_e32 v159, v159
	v_rcp_f32_e32 v161, v161
	v_rcp_f32_e32 v163, v163
	v_rcp_f32_e32 v165, v165
	v_rcp_f32_e32 v170, v170
	v_rcp_f32_e32 v171, v171
	v_rcp_f32_e32 v177, v177
	v_cvt_pk_bf16_f32 v178, v0, v161
	v_cvt_pk_bf16_f32 v180, v159, v163
	v_cvt_pk_bf16_f32 v179, v165, v171
	v_cvt_pk_bf16_f32 v181, v170, v177
	global_store_dwordx4 v[166:167], v[178:181], off offset:256
	v_ashrrev_i32_e32 v165, 31, v164
	v_lshlrev_b64 v[170:171], 14, v[164:165]
	v_pk_add_f32 v[178:179], v[120:121], v[144:145]
	v_pk_add_f32 v[180:181], v[118:119], v[142:143]
	v_med3_f32 v165, v178, s3, v236
	v_med3_f32 v178, v179, s3, v236
	v_mul_f32_e32 v178, 0xbfb8aa3b, v178
	v_exp_f32_e32 v178, v178
	v_pk_add_f32 v[182:183], v[116:117], v[140:141]
	v_pk_add_f32 v[184:185], v[114:115], v[138:139]
	v_med3_f32 v0, v180, s3, v236
	v_med3_f32 v159, v184, s3, v236
	v_med3_f32 v161, v181, s3, v236
	v_med3_f32 v163, v185, s3, v236
	v_med3_f32 v177, v182, s3, v236
	v_med3_f32 v179, v183, s3, v236
	v_add_f32_e32 v178, 1.0, v178
	v_mul_f32_e32 v0, 0xbfb8aa3b, v0
	v_mul_f32_e32 v159, 0xbfb8aa3b, v159
	v_mul_f32_e32 v161, 0xbfb8aa3b, v161
	v_mul_f32_e32 v163, 0xbfb8aa3b, v163
	v_mul_f32_e32 v165, 0xbfb8aa3b, v165
	v_mul_f32_e32 v177, 0xbfb8aa3b, v177
	v_rcp_f32_e32 v180, v178
	v_mul_f32_e32 v178, 0xbfb8aa3b, v179
	v_exp_f32_e32 v0, v0
	v_exp_f32_e32 v159, v159
	v_exp_f32_e32 v161, v161
	v_exp_f32_e32 v163, v163
	v_exp_f32_e32 v165, v165
	v_exp_f32_e32 v177, v177
	v_exp_f32_e32 v178, v178
	v_add_f32_e32 v0, 1.0, v0
	v_add_f32_e32 v159, 1.0, v159
	v_add_f32_e32 v161, 1.0, v161
	v_add_f32_e32 v163, 1.0, v163
	v_add_f32_e32 v165, 1.0, v165
	v_add_f32_e32 v177, 1.0, v177
	v_add_f32_e32 v178, 1.0, v178
	v_rcp_f32_e32 v0, v0
	v_rcp_f32_e32 v159, v159
	v_rcp_f32_e32 v161, v161
	v_rcp_f32_e32 v163, v163
	v_rcp_f32_e32 v165, v165
	v_rcp_f32_e32 v177, v177
	v_rcp_f32_e32 v181, v178
	v_lshl_add_u64 v[170:171], s[88:89], 0, v[170:171]
	v_lshl_add_u64 v[170:171], v[170:171], 0, v[168:169]
	v_cvt_pk_bf16_f32 v178, v0, v161
	v_cvt_pk_bf16_f32 v179, v165, v180
	v_cvt_pk_bf16_f32 v180, v159, v163
	v_cvt_pk_bf16_f32 v181, v177, v181
	global_store_dwordx4 v[170:171], v[178:181], off
	v_pk_add_f32 v[182:183], v[92:93], v[132:133]
	v_pk_add_f32 v[184:185], v[90:91], v[130:131]
	v_pk_add_f32 v[178:179], v[96:97], v[136:137]
	v_pk_add_f32 v[180:181], v[94:95], v[134:135]
	v_med3_f32 v165, v178, s3, v236
	v_med3_f32 v178, v179, s3, v236
	v_mul_f32_e32 v178, 0xbfb8aa3b, v178
	v_exp_f32_e32 v178, v178
	v_med3_f32 v0, v180, s3, v236
	v_med3_f32 v159, v184, s3, v236
	v_med3_f32 v161, v181, s3, v236
	v_med3_f32 v163, v185, s3, v236
	v_med3_f32 v177, v182, s3, v236
	v_med3_f32 v179, v183, s3, v236
	v_add_f32_e32 v178, 1.0, v178
	v_mul_f32_e32 v0, 0xbfb8aa3b, v0
	v_mul_f32_e32 v159, 0xbfb8aa3b, v159
	v_mul_f32_e32 v161, 0xbfb8aa3b, v161
; #define GAS __attribute__((address_space(1)))
; DI unsigned pk2(float lo, float hi) { f32x2 v = {lo, hi}; bf16x2_t b = __builtin_convertvector(v, bf16x2_t); return __builtin_bit_cast(unsigned, b); }
; DI float fast_exp2(float x) { return __builtin_amdgcn_exp2f(x); }
; DI float fast_rcp(float x) { return __builtin_amdgcn_rcpf(x); }
;     __device__ __forceinline__ void operator()(const f32x4 (&acc)[2][2][4][2], const Unit& u, int wr, int wc, int fr, int fq) const {
;     ...
;             for (int ai = 0; ai < 2; ++ai)
; #pragma unroll
;                 for (int m = 0; m < 4; ++m) { bf16_t* rowp = Gp + (size_t)(row0 + ai * HALF + m * 16) * GW + col0;
; #pragma unroll
;                     for (int bj = 0; bj < 2; ++bj) { f32x4 v0 = acc[ai][bj][m][0] + bv[bj][0], v1 = acc[ai][bj][m][1] + bv[bj][1];
; #pragma unroll
;                         for (int e = 0; e < 4; ++e) { float a = fminf(fmaxf(v0[e], -30.f), 30.f), b = fminf(fmaxf(v1[e], -30.f), 30.f);
;                             v0[e] = fast_rcp(1.f + fast_exp2(-a * LOG2E)); v1[e] = fast_rcp(1.f + fast_exp2(-b * LOG2E)); }
;                         u32x4 w; w.x = pk2(v0[0], v0[1]); w.y = pk2(v0[2], v0[3]); w.z = pk2(v1[0], v1[1]); w.w = pk2(v1[2], v1[3]);
;                         *(GAS u32x4*)(rowp + bj * HALF) = w; } }
	v_mul_f32_e32 v163, 0xbfb8aa3b, v163
	v_mul_f32_e32 v165, 0xbfb8aa3b, v165
	v_mul_f32_e32 v177, 0xbfb8aa3b, v177
	v_rcp_f32_e32 v180, v178
	v_mul_f32_e32 v178, 0xbfb8aa3b, v179
	v_exp_f32_e32 v0, v0
	v_exp_f32_e32 v159, v159
	v_exp_f32_e32 v161, v161
	v_exp_f32_e32 v163, v163
	v_exp_f32_e32 v165, v165
	v_exp_f32_e32 v177, v177
	v_exp_f32_e32 v178, v178
	v_add_f32_e32 v0, 1.0, v0
	v_add_f32_e32 v159, 1.0, v159
	v_add_f32_e32 v161, 1.0, v161
	v_add_f32_e32 v163, 1.0, v163
	v_add_f32_e32 v165, 1.0, v165
	v_add_f32_e32 v177, 1.0, v177
	v_add_f32_e32 v178, 1.0, v178
	v_rcp_f32_e32 v0, v0
	v_rcp_f32_e32 v159, v159
	v_rcp_f32_e32 v161, v161
	v_rcp_f32_e32 v163, v163
	v_rcp_f32_e32 v165, v165
	v_rcp_f32_e32 v177, v177
	v_rcp_f32_e32 v181, v178
	v_cvt_pk_bf16_f32 v178, v0, v161
	v_cvt_pk_bf16_f32 v179, v165, v180
	v_cvt_pk_bf16_f32 v180, v159, v163
	v_cvt_pk_bf16_f32 v181, v177, v181
	global_store_dwordx4 v[170:171], v[178:181], off offset:256
	v_ashrrev_i32_e32 v163, 31, v162
	v_pk_add_f32 v[182:183], v[100:101], v[140:141]
	v_pk_add_f32 v[178:179], v[104:105], v[144:145]
	v_pk_add_f32 v[180:181], v[102:103], v[142:143]
	v_med3_f32 v165, v178, s3, v236
	v_med3_f32 v178, v179, s3, v236
	v_mul_f32_e32 v178, 0xbfb8aa3b, v178
	v_exp_f32_e32 v178, v178
	v_pk_add_f32 v[184:185], v[98:99], v[138:139]
	v_lshlrev_b64 v[170:171], 14, v[162:163]
	v_med3_f32 v0, v180, s3, v236
	v_med3_f32 v159, v184, s3, v236
	v_med3_f32 v161, v181, s3, v236
	v_med3_f32 v163, v185, s3, v236
	v_med3_f32 v177, v182, s3, v236
	v_med3_f32 v179, v183, s3, v236
	v_add_f32_e32 v178, 1.0, v178
	v_mul_f32_e32 v0, 0xbfb8aa3b, v0
	v_mul_f32_e32 v159, 0xbfb8aa3b, v159
	v_mul_f32_e32 v161, 0xbfb8aa3b, v161
	v_mul_f32_e32 v163, 0xbfb8aa3b, v163
	v_mul_f32_e32 v165, 0xbfb8aa3b, v165
	v_mul_f32_e32 v177, 0xbfb8aa3b, v177
	v_rcp_f32_e32 v180, v178
	v_mul_f32_e32 v178, 0xbfb8aa3b, v179
	v_exp_f32_e32 v0, v0
	v_exp_f32_e32 v159, v159
	v_exp_f32_e32 v161, v161
	v_exp_f32_e32 v163, v163
	v_exp_f32_e32 v165, v165
	v_exp_f32_e32 v177, v177
	v_exp_f32_e32 v178, v178
	v_add_f32_e32 v0, 1.0, v0
	v_add_f32_e32 v159, 1.0, v159
	v_add_f32_e32 v161, 1.0, v161
	v_add_f32_e32 v163, 1.0, v163
	v_add_f32_e32 v165, 1.0, v165
	v_add_f32_e32 v177, 1.0, v177
	v_add_f32_e32 v178, 1.0, v178
	v_rcp_f32_e32 v0, v0
	v_rcp_f32_e32 v159, v159
	v_rcp_f32_e32 v161, v161
	v_rcp_f32_e32 v163, v163
	v_rcp_f32_e32 v165, v165
	v_rcp_f32_e32 v177, v177
	v_rcp_f32_e32 v181, v178
	v_lshl_add_u64 v[170:171], s[88:89], 0, v[170:171]
	v_lshl_add_u64 v[170:171], v[170:171], 0, v[168:169]
	v_cvt_pk_bf16_f32 v178, v0, v161
	v_cvt_pk_bf16_f32 v179, v165, v180
	v_cvt_pk_bf16_f32 v180, v159, v163
	v_cvt_pk_bf16_f32 v181, v177, v181
	global_store_dwordx4 v[170:171], v[178:181], off
	v_pk_add_f32 v[182:183], v[76:77], v[132:133]
	v_pk_add_f32 v[184:185], v[74:75], v[130:131]
	v_pk_add_f32 v[178:179], v[80:81], v[136:137]
	v_pk_add_f32 v[180:181], v[78:79], v[134:135]
	v_med3_f32 v165, v178, s3, v236
	v_med3_f32 v178, v179, s3, v236
	v_mul_f32_e32 v178, 0xbfb8aa3b, v178
	v_exp_f32_e32 v178, v178
	v_med3_f32 v0, v180, s3, v236
	v_med3_f32 v159, v184, s3, v236
	v_med3_f32 v161, v181, s3, v236
	v_med3_f32 v163, v185, s3, v236
	v_med3_f32 v177, v182, s3, v236
	v_med3_f32 v179, v183, s3, v236
	v_add_f32_e32 v178, 1.0, v178
	v_mul_f32_e32 v0, 0xbfb8aa3b, v0
	v_mul_f32_e32 v159, 0xbfb8aa3b, v159
	v_mul_f32_e32 v161, 0xbfb8aa3b, v161
	v_mul_f32_e32 v163, 0xbfb8aa3b, v163
	v_mul_f32_e32 v165, 0xbfb8aa3b, v165
	v_mul_f32_e32 v177, 0xbfb8aa3b, v177
	v_rcp_f32_e32 v180, v178
	v_mul_f32_e32 v178, 0xbfb8aa3b, v179
	v_exp_f32_e32 v0, v0
	v_exp_f32_e32 v159, v159
	v_exp_f32_e32 v161, v161
	v_exp_f32_e32 v163, v163
	v_exp_f32_e32 v165, v165
	v_exp_f32_e32 v177, v177
	v_exp_f32_e32 v178, v178
	v_add_f32_e32 v0, 1.0, v0
	v_add_f32_e32 v159, 1.0, v159
	v_add_f32_e32 v161, 1.0, v161
	v_add_f32_e32 v163, 1.0, v163
	v_add_f32_e32 v165, 1.0, v165
	v_add_f32_e32 v177, 1.0, v177
	v_add_f32_e32 v178, 1.0, v178
	v_rcp_f32_e32 v0, v0
	v_rcp_f32_e32 v159, v159
	v_rcp_f32_e32 v161, v161
	v_rcp_f32_e32 v163, v163
	v_rcp_f32_e32 v165, v165
	v_rcp_f32_e32 v177, v177
	v_rcp_f32_e32 v181, v178
	v_cvt_pk_bf16_f32 v178, v0, v161
	v_cvt_pk_bf16_f32 v179, v165, v180
	v_cvt_pk_bf16_f32 v180, v159, v163
	v_cvt_pk_bf16_f32 v181, v177, v181
	v_ashrrev_i32_e32 v161, 31, v160
	global_store_dwordx4 v[170:171], v[178:181], off offset:256
	v_lshlrev_b64 v[170:171], 14, v[160:161]
	v_lshl_add_u64 v[170:171], s[88:89], 0, v[170:171]
	v_lshl_add_u64 v[168:169], v[170:171], 0, v[168:169]
	v_pk_add_f32 v[170:171], v[88:89], v[144:145]
	v_pk_add_f32 v[178:179], v[86:87], v[142:143]
	v_pk_add_f32 v[180:181], v[84:85], v[140:141]
	v_pk_add_f32 v[182:183], v[82:83], v[138:139]
	v_med3_f32 v0, v178, s3, v236
	v_med3_f32 v159, v182, s3, v236
	v_med3_f32 v161, v179, s3, v236
	v_med3_f32 v163, v183, s3, v236
	v_med3_f32 v165, v170, s3, v236
	v_med3_f32 v170, v180, s3, v236
	v_med3_f32 v171, v171, s3, v236
	v_med3_f32 v177, v181, s3, v236
	v_mul_f32_e32 v0, 0xbfb8aa3b, v0
	v_mul_f32_e32 v159, 0xbfb8aa3b, v159
	v_mul_f32_e32 v161, 0xbfb8aa3b, v161
	v_mul_f32_e32 v163, 0xbfb8aa3b, v163
	v_mul_f32_e32 v165, 0xbfb8aa3b, v165
	v_mul_f32_e32 v170, 0xbfb8aa3b, v170
	v_mul_f32_e32 v171, 0xbfb8aa3b, v171
	v_mul_f32_e32 v177, 0xbfb8aa3b, v177
	v_exp_f32_e32 v0, v0
	v_exp_f32_e32 v159, v159
	v_exp_f32_e32 v161, v161
	v_exp_f32_e32 v163, v163
	v_exp_f32_e32 v165, v165
	v_exp_f32_e32 v170, v170
	v_exp_f32_e32 v171, v171
	v_exp_f32_e32 v177, v177
	v_add_f32_e32 v0, 1.0, v0
	v_add_f32_e32 v159, 1.0, v159
	v_add_f32_e32 v161, 1.0, v161
	v_add_f32_e32 v163, 1.0, v163
	v_add_f32_e32 v165, 1.0, v165
	v_add_f32_e32 v170, 1.0, v170
; #define GAS __attribute__((address_space(1)))
; DI unsigned pk2(float lo, float hi) { f32x2 v = {lo, hi}; bf16x2_t b = __builtin_convertvector(v, bf16x2_t); return __builtin_bit_cast(unsigned, b); }
; DI float fast_exp2(float x) { return __builtin_amdgcn_exp2f(x); }
; DI float fast_rcp(float x) { return __builtin_amdgcn_rcpf(x); }
;     __device__ __forceinline__ void operator()(const f32x4 (&acc)[2][2][4][2], const Unit& u, int wr, int wc, int fr, int fq) const {
;     ...
;             for (int ai = 0; ai < 2; ++ai)
; #pragma unroll
;                 for (int m = 0; m < 4; ++m) { bf16_t* rowp = Gp + (size_t)(row0 + ai * HALF + m * 16) * GW + col0;
; #pragma unroll
;                     for (int bj = 0; bj < 2; ++bj) { f32x4 v0 = acc[ai][bj][m][0] + bv[bj][0], v1 = acc[ai][bj][m][1] + bv[bj][1];
; #pragma unroll
;                         for (int e = 0; e < 4; ++e) { float a = fminf(fmaxf(v0[e], -30.f), 30.f), b = fminf(fmaxf(v1[e], -30.f), 30.f);
;                             v0[e] = fast_rcp(1.f + fast_exp2(-a * LOG2E)); v1[e] = fast_rcp(1.f + fast_exp2(-b * LOG2E)); }
;                         u32x4 w; w.x = pk2(v0[0], v0[1]); w.y = pk2(v0[2], v0[3]); w.z = pk2(v1[0], v1[1]); w.w = pk2(v1[2], v1[3]);
;                         *(GAS u32x4*)(rowp + bj * HALF) = w; } }
	v_add_f32_e32 v171, 1.0, v171
	v_add_f32_e32 v177, 1.0, v177
	v_rcp_f32_e32 v0, v0
	v_rcp_f32_e32 v159, v159
	v_rcp_f32_e32 v161, v161
	v_rcp_f32_e32 v163, v163
	v_rcp_f32_e32 v165, v165
	v_rcp_f32_e32 v170, v170
	v_rcp_f32_e32 v171, v171
	v_rcp_f32_e32 v177, v177
	v_cvt_pk_bf16_f32 v178, v0, v161
	v_cvt_pk_bf16_f32 v180, v159, v163
	v_cvt_pk_bf16_f32 v179, v165, v171
	v_cvt_pk_bf16_f32 v181, v170, v177
	global_store_dwordx4 v[168:169], v[178:181], off
	v_pk_add_f32 v[170:171], v[72:73], v[136:137]
	v_pk_add_f32 v[182:183], v[66:67], v[130:131]
	v_pk_add_f32 v[178:179], v[70:71], v[134:135]
	v_pk_add_f32 v[180:181], v[68:69], v[132:133]
	v_med3_f32 v0, v178, s3, v236
	v_med3_f32 v159, v182, s3, v236
	v_med3_f32 v161, v179, s3, v236
	v_med3_f32 v163, v183, s3, v236
	v_med3_f32 v165, v170, s3, v236
	v_med3_f32 v170, v180, s3, v236
	v_med3_f32 v171, v171, s3, v236
	v_med3_f32 v177, v181, s3, v236
	v_mul_f32_e32 v0, 0xbfb8aa3b, v0
	v_mul_f32_e32 v159, 0xbfb8aa3b, v159
	v_mul_f32_e32 v161, 0xbfb8aa3b, v161
	v_mul_f32_e32 v163, 0xbfb8aa3b, v163
	v_mul_f32_e32 v165, 0xbfb8aa3b, v165
	v_mul_f32_e32 v170, 0xbfb8aa3b, v170
	v_mul_f32_e32 v171, 0xbfb8aa3b, v171
	v_mul_f32_e32 v177, 0xbfb8aa3b, v177
	v_exp_f32_e32 v0, v0
	v_exp_f32_e32 v159, v159
	v_exp_f32_e32 v161, v161
	v_exp_f32_e32 v163, v163
	v_exp_f32_e32 v165, v165
	v_exp_f32_e32 v170, v170
	v_exp_f32_e32 v171, v171
	v_exp_f32_e32 v177, v177
	v_add_f32_e32 v0, 1.0, v0
	v_add_f32_e32 v159, 1.0, v159
	v_add_f32_e32 v161, 1.0, v161
	v_add_f32_e32 v163, 1.0, v163
	v_add_f32_e32 v165, 1.0, v165
	v_add_f32_e32 v170, 1.0, v170
	v_add_f32_e32 v171, 1.0, v171
	v_add_f32_e32 v177, 1.0, v177
	v_rcp_f32_e32 v0, v0
	v_rcp_f32_e32 v159, v159
	v_rcp_f32_e32 v161, v161
	v_rcp_f32_e32 v163, v163
	v_rcp_f32_e32 v165, v165
	v_rcp_f32_e32 v170, v170
	v_rcp_f32_e32 v171, v171
	v_rcp_f32_e32 v177, v177
	v_cvt_pk_bf16_f32 v178, v0, v161
	v_cvt_pk_bf16_f32 v180, v159, v163
	v_cvt_pk_bf16_f32 v179, v165, v171
	v_cvt_pk_bf16_f32 v181, v170, v177
	global_store_dwordx4 v[168:169], v[178:181], off offset:256
	v_pk_add_f32 v[170:171], v[64:65], v[144:145]
	v_pk_add_f32 v[182:183], v[58:59], v[138:139]
	v_pk_add_f32 v[180:181], v[60:61], v[140:141]
	v_pk_add_f32 v[178:179], v[62:63], v[142:143]
	v_med3_f32 v165, v170, s3, v236
	v_med3_f32 v170, v180, s3, v236
	v_med3_f32 v177, v181, s3, v236
	v_med3_f32 v0, v178, s3, v236
	v_med3_f32 v159, v182, s3, v236
	v_med3_f32 v161, v179, s3, v236
	v_med3_f32 v163, v183, s3, v236
	v_mul_f32_e32 v170, 0xbfb8aa3b, v170
	v_med3_f32 v171, v171, s3, v236
	v_mul_f32_e32 v177, 0xbfb8aa3b, v177
	v_mul_f32_e32 v0, 0xbfb8aa3b, v0
	v_mul_f32_e32 v159, 0xbfb8aa3b, v159
	v_mul_f32_e32 v161, 0xbfb8aa3b, v161
	v_mul_f32_e32 v163, 0xbfb8aa3b, v163
	v_mul_f32_e32 v165, 0xbfb8aa3b, v165
	v_exp_f32_e32 v170, v170
	v_mul_f32_e32 v171, 0xbfb8aa3b, v171
	v_exp_f32_e32 v177, v177
	v_exp_f32_e32 v0, v0
	v_exp_f32_e32 v159, v159
	v_exp_f32_e32 v161, v161
	v_exp_f32_e32 v163, v163
	v_exp_f32_e32 v165, v165
	v_exp_f32_e32 v171, v171
	v_add_f32_e32 v170, 1.0, v170
	v_add_f32_e32 v177, 1.0, v177
	v_add_f32_e32 v0, 1.0, v0
	v_add_f32_e32 v159, 1.0, v159
	v_add_f32_e32 v161, 1.0, v161
	v_add_f32_e32 v163, 1.0, v163
	v_add_f32_e32 v165, 1.0, v165
	v_rcp_f32_e32 v170, v170
	v_add_f32_e32 v171, 1.0, v171
	v_rcp_f32_e32 v177, v177
	v_rcp_f32_e32 v0, v0
	v_rcp_f32_e32 v159, v159
	v_rcp_f32_e32 v161, v161
	v_rcp_f32_e32 v163, v163
	v_rcp_f32_e32 v165, v165
	v_rcp_f32_e32 v171, v171
	v_cvt_pk_bf16_f32 v181, v170, v177
	v_add_co_u32_e32 v170, vcc, s13, v166
	v_cvt_pk_bf16_f32 v178, v0, v161
	v_cvt_pk_bf16_f32 v179, v165, v171
	v_cvt_pk_bf16_f32 v180, v159, v163
	v_addc_co_u32_e32 v171, vcc, 0, v167, vcc
	global_store_dwordx4 v[170:171], v[178:181], off
	v_pk_add_f32 v[170:171], v[48:49], v[136:137]
	v_pk_add_f32 v[182:183], v[42:43], v[130:131]
	v_pk_add_f32 v[178:179], v[46:47], v[134:135]
	v_pk_add_f32 v[180:181], v[44:45], v[132:133]
	v_med3_f32 v0, v178, s3, v236
	v_med3_f32 v159, v182, s3, v236
	v_med3_f32 v161, v179, s3, v236
	v_med3_f32 v163, v183, s3, v236
	v_med3_f32 v165, v170, s3, v236
	v_med3_f32 v170, v180, s3, v236
	v_med3_f32 v171, v171, s3, v236
	v_med3_f32 v177, v181, s3, v236
	v_mul_f32_e32 v0, 0xbfb8aa3b, v0
	v_mul_f32_e32 v159, 0xbfb8aa3b, v159
	v_mul_f32_e32 v161, 0xbfb8aa3b, v161
	v_mul_f32_e32 v163, 0xbfb8aa3b, v163
	v_mul_f32_e32 v165, 0xbfb8aa3b, v165
	v_mul_f32_e32 v170, 0xbfb8aa3b, v170
	v_mul_f32_e32 v171, 0xbfb8aa3b, v171
	v_mul_f32_e32 v177, 0xbfb8aa3b, v177
	v_exp_f32_e32 v0, v0
	v_exp_f32_e32 v159, v159
	v_exp_f32_e32 v161, v161
	v_exp_f32_e32 v163, v163
	v_exp_f32_e32 v165, v165
	v_exp_f32_e32 v170, v170
	v_exp_f32_e32 v171, v171
	v_exp_f32_e32 v177, v177
	v_add_f32_e32 v0, 1.0, v0
	v_add_f32_e32 v159, 1.0, v159
	v_add_f32_e32 v161, 1.0, v161
	v_add_f32_e32 v163, 1.0, v163
	v_add_f32_e32 v165, 1.0, v165
	v_add_f32_e32 v170, 1.0, v170
	v_add_f32_e32 v171, 1.0, v171
	v_add_f32_e32 v177, 1.0, v177
	v_rcp_f32_e32 v0, v0
	v_rcp_f32_e32 v159, v159
	v_rcp_f32_e32 v161, v161
	v_rcp_f32_e32 v163, v163
	v_rcp_f32_e32 v165, v165
	v_rcp_f32_e32 v170, v170
	v_rcp_f32_e32 v171, v171
	v_rcp_f32_e32 v177, v177
	v_lshl_add_u64 v[168:169], v[166:167], 0, s[18:19]
	v_cvt_pk_bf16_f32 v178, v0, v161
	v_cvt_pk_bf16_f32 v179, v165, v171
	v_cvt_pk_bf16_f32 v180, v159, v163
	v_cvt_pk_bf16_f32 v181, v170, v177
	global_store_dwordx4 v[168:169], v[178:181], off offset:256
	v_pk_add_f32 v[170:171], v[56:57], v[144:145]
	v_pk_add_f32 v[182:183], v[50:51], v[138:139]
	v_pk_add_f32 v[180:181], v[52:53], v[140:141]
	v_pk_add_f32 v[178:179], v[54:55], v[142:143]
	v_med3_f32 v165, v170, s3, v236
	v_med3_f32 v170, v180, s3, v236
; #define GAS __attribute__((address_space(1)))
; DI unsigned pk2(float lo, float hi) { f32x2 v = {lo, hi}; bf16x2_t b = __builtin_convertvector(v, bf16x2_t); return __builtin_bit_cast(unsigned, b); }
; DI float fast_exp2(float x) { return __builtin_amdgcn_exp2f(x); }
; DI float fast_rcp(float x) { return __builtin_amdgcn_rcpf(x); }
;     __device__ __forceinline__ void operator()(const f32x4 (&acc)[2][2][4][2], const Unit& u, int wr, int wc, int fr, int fq) const {
;     ...
;             for (int ai = 0; ai < 2; ++ai)
; #pragma unroll
;                 for (int m = 0; m < 4; ++m) { bf16_t* rowp = Gp + (size_t)(row0 + ai * HALF + m * 16) * GW + col0;
; #pragma unroll
;                     for (int bj = 0; bj < 2; ++bj) { f32x4 v0 = acc[ai][bj][m][0] + bv[bj][0], v1 = acc[ai][bj][m][1] + bv[bj][1];
; #pragma unroll
;                         for (int e = 0; e < 4; ++e) { float a = fminf(fmaxf(v0[e], -30.f), 30.f), b = fminf(fmaxf(v1[e], -30.f), 30.f);
;                             v0[e] = fast_rcp(1.f + fast_exp2(-a * LOG2E)); v1[e] = fast_rcp(1.f + fast_exp2(-b * LOG2E)); }
;                         u32x4 w; w.x = pk2(v0[0], v0[1]); w.y = pk2(v0[2], v0[3]); w.z = pk2(v1[0], v1[1]); w.w = pk2(v1[2], v1[3]);
;                         *(GAS u32x4*)(rowp + bj * HALF) = w; } }
	v_med3_f32 v177, v181, s3, v236
	v_med3_f32 v0, v178, s3, v236
	v_med3_f32 v159, v182, s3, v236
	v_med3_f32 v161, v179, s3, v236
	v_med3_f32 v163, v183, s3, v236
	v_mul_f32_e32 v170, 0xbfb8aa3b, v170
	v_med3_f32 v171, v171, s3, v236
	v_mul_f32_e32 v177, 0xbfb8aa3b, v177
	v_mul_f32_e32 v0, 0xbfb8aa3b, v0
	v_mul_f32_e32 v159, 0xbfb8aa3b, v159
	v_mul_f32_e32 v161, 0xbfb8aa3b, v161
	v_mul_f32_e32 v163, 0xbfb8aa3b, v163
	v_mul_f32_e32 v165, 0xbfb8aa3b, v165
	v_exp_f32_e32 v170, v170
	v_mul_f32_e32 v171, 0xbfb8aa3b, v171
	v_exp_f32_e32 v177, v177
	v_exp_f32_e32 v0, v0
	v_exp_f32_e32 v159, v159
	v_exp_f32_e32 v161, v161
	v_exp_f32_e32 v163, v163
	v_exp_f32_e32 v165, v165
	v_exp_f32_e32 v171, v171
	v_add_f32_e32 v170, 1.0, v170
	v_add_f32_e32 v177, 1.0, v177
	v_add_f32_e32 v0, 1.0, v0
	v_add_f32_e32 v159, 1.0, v159
	v_add_f32_e32 v161, 1.0, v161
	v_add_f32_e32 v163, 1.0, v163
	v_add_f32_e32 v165, 1.0, v165
	v_rcp_f32_e32 v170, v170
	v_add_f32_e32 v171, 1.0, v171
	v_rcp_f32_e32 v177, v177
	v_rcp_f32_e32 v0, v0
	v_rcp_f32_e32 v159, v159
	v_rcp_f32_e32 v161, v161
	v_rcp_f32_e32 v163, v163
	v_rcp_f32_e32 v165, v165
	v_rcp_f32_e32 v171, v171
	s_mov_b32 s13, 0x240000
	v_cvt_pk_bf16_f32 v181, v170, v177
	v_add_co_u32_e32 v170, vcc, s13, v166
	v_cvt_pk_bf16_f32 v178, v0, v161
	v_cvt_pk_bf16_f32 v179, v165, v171
	v_cvt_pk_bf16_f32 v180, v159, v163
	v_addc_co_u32_e32 v171, vcc, 0, v167, vcc
	global_store_dwordx4 v[170:171], v[178:181], off
	v_pk_add_f32 v[170:171], v[32:33], v[136:137]
	v_pk_add_f32 v[182:183], v[26:27], v[130:131]
	v_pk_add_f32 v[178:179], v[30:31], v[134:135]
	v_pk_add_f32 v[180:181], v[28:29], v[132:133]
	v_med3_f32 v0, v178, s3, v236
	v_med3_f32 v159, v182, s3, v236
	v_med3_f32 v161, v179, s3, v236
	v_med3_f32 v163, v183, s3, v236
	v_med3_f32 v165, v170, s3, v236
	v_med3_f32 v170, v180, s3, v236
	v_med3_f32 v171, v171, s3, v236
	v_med3_f32 v177, v181, s3, v236
	v_mul_f32_e32 v0, 0xbfb8aa3b, v0
	v_mul_f32_e32 v159, 0xbfb8aa3b, v159
	v_mul_f32_e32 v161, 0xbfb8aa3b, v161
	v_mul_f32_e32 v163, 0xbfb8aa3b, v163
	v_mul_f32_e32 v165, 0xbfb8aa3b, v165
	v_mul_f32_e32 v170, 0xbfb8aa3b, v170
	v_mul_f32_e32 v171, 0xbfb8aa3b, v171
	v_mul_f32_e32 v177, 0xbfb8aa3b, v177
	v_exp_f32_e32 v0, v0
	v_exp_f32_e32 v159, v159
	v_exp_f32_e32 v161, v161
	v_exp_f32_e32 v163, v163
	v_exp_f32_e32 v165, v165
	v_exp_f32_e32 v170, v170
	v_exp_f32_e32 v171, v171
	v_exp_f32_e32 v177, v177
	v_add_f32_e32 v0, 1.0, v0
	v_add_f32_e32 v159, 1.0, v159
	v_add_f32_e32 v161, 1.0, v161
	v_add_f32_e32 v163, 1.0, v163
	v_add_f32_e32 v165, 1.0, v165
	v_add_f32_e32 v170, 1.0, v170
	v_add_f32_e32 v171, 1.0, v171
	v_add_f32_e32 v177, 1.0, v177
	v_rcp_f32_e32 v0, v0
	v_rcp_f32_e32 v159, v159
	v_rcp_f32_e32 v161, v161
	v_rcp_f32_e32 v163, v163
	v_rcp_f32_e32 v165, v165
	v_rcp_f32_e32 v170, v170
	v_rcp_f32_e32 v171, v171
	v_rcp_f32_e32 v177, v177
	s_mov_b64 s[18:19], 0x240000
	v_lshl_add_u64 v[168:169], v[166:167], 0, s[18:19]
	v_cvt_pk_bf16_f32 v178, v0, v161
	v_cvt_pk_bf16_f32 v179, v165, v171
	v_cvt_pk_bf16_f32 v180, v159, v163
	v_cvt_pk_bf16_f32 v181, v170, v177
	global_store_dwordx4 v[168:169], v[178:181], off offset:256
	v_pk_add_f32 v[170:171], v[40:41], v[144:145]
	v_pk_add_f32 v[182:183], v[34:35], v[138:139]
	v_pk_add_f32 v[180:181], v[36:37], v[140:141]
	v_pk_add_f32 v[178:179], v[38:39], v[142:143]
	v_med3_f32 v165, v170, s3, v236
	v_med3_f32 v170, v180, s3, v236
	v_med3_f32 v177, v181, s3, v236
	v_med3_f32 v0, v178, s3, v236
	v_med3_f32 v159, v182, s3, v236
	v_med3_f32 v161, v179, s3, v236
	v_med3_f32 v163, v183, s3, v236
	v_mul_f32_e32 v170, 0xbfb8aa3b, v170
	v_med3_f32 v171, v171, s3, v236
	v_mul_f32_e32 v177, 0xbfb8aa3b, v177
	v_mul_f32_e32 v0, 0xbfb8aa3b, v0
	v_mul_f32_e32 v159, 0xbfb8aa3b, v159
	v_mul_f32_e32 v161, 0xbfb8aa3b, v161
	v_mul_f32_e32 v163, 0xbfb8aa3b, v163
	v_mul_f32_e32 v165, 0xbfb8aa3b, v165
	v_exp_f32_e32 v170, v170
	v_mul_f32_e32 v171, 0xbfb8aa3b, v171
	v_exp_f32_e32 v177, v177
	v_exp_f32_e32 v0, v0
	v_exp_f32_e32 v159, v159
	v_exp_f32_e32 v161, v161
	v_exp_f32_e32 v163, v163
	v_exp_f32_e32 v165, v165
	v_exp_f32_e32 v171, v171
	v_add_f32_e32 v170, 1.0, v170
	v_add_f32_e32 v177, 1.0, v177
	v_add_f32_e32 v0, 1.0, v0
	v_add_f32_e32 v159, 1.0, v159
	v_add_f32_e32 v161, 1.0, v161
	v_add_f32_e32 v163, 1.0, v163
	v_add_f32_e32 v165, 1.0, v165
	v_rcp_f32_e32 v170, v170
	v_add_f32_e32 v171, 1.0, v171
	v_rcp_f32_e32 v177, v177
	v_rcp_f32_e32 v0, v0
	v_rcp_f32_e32 v159, v159
	v_rcp_f32_e32 v161, v161
	v_rcp_f32_e32 v163, v163
	v_rcp_f32_e32 v165, v165
	v_rcp_f32_e32 v171, v171
	s_mov_b32 s13, 0x280000
	v_cvt_pk_bf16_f32 v181, v170, v177
	v_add_co_u32_e32 v170, vcc, s13, v166
	v_cvt_pk_bf16_f32 v178, v0, v161
	v_cvt_pk_bf16_f32 v179, v165, v171
	v_cvt_pk_bf16_f32 v180, v159, v163
	v_addc_co_u32_e32 v171, vcc, 0, v167, vcc
	global_store_dwordx4 v[170:171], v[178:181], off
	v_pk_add_f32 v[140:141], v[20:21], v[140:141]
	v_pk_add_f32 v[138:139], v[18:19], v[138:139]
; #define GAS __attribute__((address_space(1)))
; DI unsigned pk2(float lo, float hi) { f32x2 v = {lo, hi}; bf16x2_t b = __builtin_convertvector(v, bf16x2_t); return __builtin_bit_cast(unsigned, b); }
; DI float fast_exp2(float x) { return __builtin_amdgcn_exp2f(x); }
; DI float fast_rcp(float x) { return __builtin_amdgcn_rcpf(x); }
;     __device__ __forceinline__ void operator()(const f32x4 (&acc)[2][2][4][2], const Unit& u, int wr, int wc, int fr, int fq) const {
;     ...
;             for (int ai = 0; ai < 2; ++ai)
; #pragma unroll
;                 for (int m = 0; m < 4; ++m) { bf16_t* rowp = Gp + (size_t)(row0 + ai * HALF + m * 16) * GW + col0;
; #pragma unroll
;                     for (int bj = 0; bj < 2; ++bj) { f32x4 v0 = acc[ai][bj][m][0] + bv[bj][0], v1 = acc[ai][bj][m][1] + bv[bj][1];
; #pragma unroll
;                         for (int e = 0; e < 4; ++e) { float a = fminf(fmaxf(v0[e], -30.f), 30.f), b = fminf(fmaxf(v1[e], -30.f), 30.f);
;                             v0[e] = fast_rcp(1.f + fast_exp2(-a * LOG2E)); v1[e] = fast_rcp(1.f + fast_exp2(-b * LOG2E)); }
;                         u32x4 w; w.x = pk2(v0[0], v0[1]); w.y = pk2(v0[2], v0[3]); w.z = pk2(v1[0], v1[1]); w.w = pk2(v1[2], v1[3]);
;                         *(GAS u32x4*)(rowp + bj * HALF) = w; } }
	v_pk_add_f32 v[178:179], v[14:15], v[134:135]
	v_med3_f32 v138, v138, s3, v236
	v_med3_f32 v0, v178, s3, v236
	v_med3_f32 v161, v179, s3, v236
	v_mul_f32_e32 v0, 0xbfb8aa3b, v0
	v_mul_f32_e32 v161, 0xbfb8aa3b, v161
	v_exp_f32_e32 v0, v0
	v_exp_f32_e32 v161, v161
	v_med3_f32 v139, v139, s3, v236
	v_med3_f32 v140, v140, s3, v236
	v_mul_f32_e32 v138, 0xbfb8aa3b, v138
	v_mul_f32_e32 v139, 0xbfb8aa3b, v139
	v_mul_f32_e32 v140, 0xbfb8aa3b, v140
	v_add_f32_e32 v0, 1.0, v0
	v_add_f32_e32 v161, 1.0, v161
	v_exp_f32_e32 v138, v138
	v_exp_f32_e32 v139, v139
	v_exp_f32_e32 v140, v140
	v_rcp_f32_e32 v0, v0
	v_rcp_f32_e32 v161, v161
	v_pk_add_f32 v[144:145], v[24:25], v[144:145]
	v_pk_add_f32 v[142:143], v[22:23], v[142:143]
	v_add_f32_e32 v138, 1.0, v138
	v_add_f32_e32 v139, 1.0, v139
	v_add_f32_e32 v140, 1.0, v140
	v_cvt_pk_bf16_f32 v178, v0, v161
	v_med3_f32 v0, v142, s3, v236
	v_rcp_f32_e32 v142, v138
	v_med3_f32 v138, v143, s3, v236
	v_rcp_f32_e32 v143, v139
	v_med3_f32 v139, v144, s3, v236
	v_rcp_f32_e32 v144, v140
	v_med3_f32 v140, v145, s3, v236
	v_mul_f32_e32 v139, 0xbfb8aa3b, v139
	v_med3_f32 v141, v141, s3, v236
	v_mul_f32_e32 v140, 0xbfb8aa3b, v140
	v_mul_f32_e32 v0, 0xbfb8aa3b, v0
	v_mul_f32_e32 v138, 0xbfb8aa3b, v138
	v_exp_f32_e32 v139, v139
	v_exp_f32_e32 v140, v140
	v_mul_f32_e32 v141, 0xbfb8aa3b, v141
	v_exp_f32_e32 v0, v0
	v_exp_f32_e32 v138, v138
	v_exp_f32_e32 v141, v141
	v_pk_add_f32 v[180:181], v[12:13], v[132:133]
	v_pk_add_f32 v[182:183], v[10:11], v[130:131]
	v_pk_add_f32 v[132:133], v[4:5], v[132:133]
	v_pk_add_f32 v[130:131], v[2:3], v[130:131]
	v_add_f32_e32 v139, 1.0, v139
	v_add_f32_e32 v140, 1.0, v140
	v_med3_f32 v130, v130, s3, v236
	v_med3_f32 v131, v131, s3, v236
	v_med3_f32 v132, v132, s3, v236
	v_add_f32_e32 v0, 1.0, v0
	v_add_f32_e32 v138, 1.0, v138
	v_rcp_f32_e32 v139, v139
	v_rcp_f32_e32 v140, v140
	v_add_f32_e32 v141, 1.0, v141
	v_mul_f32_e32 v130, 0xbfb8aa3b, v130
	v_mul_f32_e32 v131, 0xbfb8aa3b, v131
	v_mul_f32_e32 v132, 0xbfb8aa3b, v132
	v_rcp_f32_e32 v0, v0
	v_rcp_f32_e32 v138, v138
	v_rcp_f32_e32 v141, v141
	v_exp_f32_e32 v130, v130
	v_exp_f32_e32 v131, v131
	v_exp_f32_e32 v132, v132
	s_mov_b32 s13, 0x2c0000
	v_pk_add_f32 v[170:171], v[16:17], v[136:137]
	v_cvt_pk_bf16_f32 v139, v139, v140
	v_cvt_pk_bf16_f32 v140, v142, v143
	v_add_co_u32_e32 v142, vcc, s13, v166
	v_med3_f32 v159, v182, s3, v236
	v_med3_f32 v163, v183, s3, v236
	v_med3_f32 v165, v170, s3, v236
	v_med3_f32 v170, v180, s3, v236
	v_med3_f32 v171, v171, s3, v236
	v_med3_f32 v177, v181, s3, v236
	v_cvt_pk_bf16_f32 v138, v0, v138
	v_cvt_pk_bf16_f32 v141, v144, v141
	v_addc_co_u32_e32 v143, vcc, 0, v167, vcc
	v_pk_add_f32 v[136:137], v[8:9], v[136:137]
	v_pk_add_f32 v[134:135], v[6:7], v[134:135]
	v_add_f32_e32 v130, 1.0, v130
	v_add_f32_e32 v131, 1.0, v131
	v_add_f32_e32 v132, 1.0, v132
	v_mul_f32_e32 v159, 0xbfb8aa3b, v159
	v_mul_f32_e32 v163, 0xbfb8aa3b, v163
	v_mul_f32_e32 v165, 0xbfb8aa3b, v165
	v_mul_f32_e32 v170, 0xbfb8aa3b, v170
	v_mul_f32_e32 v171, 0xbfb8aa3b, v171
	v_mul_f32_e32 v177, 0xbfb8aa3b, v177
	global_store_dwordx4 v[142:143], v[138:141], off
	v_med3_f32 v0, v134, s3, v236
	v_rcp_f32_e32 v134, v132
	v_rcp_f32_e32 v138, v130
	v_med3_f32 v130, v135, s3, v236
	v_rcp_f32_e32 v139, v131
	v_med3_f32 v131, v136, s3, v236
	v_med3_f32 v132, v137, s3, v236
	v_exp_f32_e32 v159, v159
	v_exp_f32_e32 v163, v163
	v_exp_f32_e32 v165, v165
	v_exp_f32_e32 v170, v170
	v_exp_f32_e32 v171, v171
	v_exp_f32_e32 v177, v177
	v_mul_f32_e32 v0, 0xbfb8aa3b, v0
	v_mul_f32_e32 v130, 0xbfb8aa3b, v130
	v_mul_f32_e32 v131, 0xbfb8aa3b, v131
	v_mul_f32_e32 v132, 0xbfb8aa3b, v132
	v_exp_f32_e32 v0, v0
	v_exp_f32_e32 v130, v130
	v_exp_f32_e32 v131, v131
	v_exp_f32_e32 v132, v132
	v_med3_f32 v133, v133, s3, v236
	v_add_f32_e32 v159, 1.0, v159
	v_add_f32_e32 v163, 1.0, v163
	v_add_f32_e32 v165, 1.0, v165
	v_add_f32_e32 v170, 1.0, v170
	v_add_f32_e32 v171, 1.0, v171
	v_add_f32_e32 v177, 1.0, v177
	v_mul_f32_e32 v133, 0xbfb8aa3b, v133
	v_rcp_f32_e32 v159, v159
	v_rcp_f32_e32 v163, v163
	v_rcp_f32_e32 v165, v165
	v_rcp_f32_e32 v170, v170
	v_rcp_f32_e32 v171, v171
	v_rcp_f32_e32 v177, v177
	v_add_f32_e32 v0, 1.0, v0
	v_add_f32_e32 v130, 1.0, v130
	v_add_f32_e32 v131, 1.0, v131
	v_add_f32_e32 v132, 1.0, v132
	v_exp_f32_e32 v133, v133
	v_rcp_f32_e32 v0, v0
	v_rcp_f32_e32 v130, v130
	v_rcp_f32_e32 v131, v131
	v_rcp_f32_e32 v132, v132
	s_mov_b64 s[18:19], 0x280000
	v_lshl_add_u64 v[168:169], v[166:167], 0, s[18:19]
	v_cvt_pk_bf16_f32 v179, v165, v171
	v_cvt_pk_bf16_f32 v180, v159, v163
	v_cvt_pk_bf16_f32 v181, v170, v177
	s_mov_b64 s[18:19], 0x2c0000
	v_add_f32_e32 v133, 1.0, v133
	global_store_dwordx4 v[168:169], v[178:181], off offset:256
	v_lshl_add_u64 v[168:169], v[166:167], 0, s[18:19]
	v_rcp_f32_e32 v135, v133
	v_cvt_pk_bf16_f32 v130, v0, v130
	v_cvt_pk_bf16_f32 v131, v131, v132
	v_cvt_pk_bf16_f32 v132, v138, v139
	s_mov_b64 s[18:19], 0
